# select_row probe loop: threshold / bit / candidate kept in SGPRs, compares take the candidate as SGPR operand
# speedup vs baseline: 1.0066x; 1.0066x over previous
; DI void select_row(const float* SC, unsigned* dmask, int b, int t, int lane) {
;     ...
;     if (!hit) {
;     ...
;             const unsigned cand = T | (1u << bit); int cnt; SEL_COUNT(cand, cnt);
;             if (cnt >= 256) { T = cand; if (cnt == 256) { hit = true; break; } }
;         }
;     }
.LBB0_571:
	s_mov_b64 s[8:9], 0
	s_mov_b32 s56, s14
	s_mov_b32 s57, s80
.LBB0_574:
	s_lshl_b32 s66, 1, s57
	s_or_b32 s66, s66, s56
	v_mov_b32_e32 v4, 0
	v_cmp_le_u32_e32 vcc, s66, v11
	v_addc_co_u32_e32 v4, vcc, 0, v4, vcc
	v_cmp_le_u32_e32 vcc, s66, v10
	v_addc_co_u32_e32 v4, vcc, 0, v4, vcc
	v_cmp_le_u32_e32 vcc, s66, v121
	v_addc_co_u32_e32 v4, vcc, 0, v4, vcc
	v_cmp_le_u32_e32 vcc, s66, v9
	v_addc_co_u32_e32 v4, vcc, 0, v4, vcc
	v_cmp_le_u32_e32 vcc, s66, v7
	v_addc_co_u32_e32 v4, vcc, 0, v4, vcc
	v_cmp_le_u32_e32 vcc, s66, v6
	v_addc_co_u32_e32 v4, vcc, 0, v4, vcc
	v_cmp_le_u32_e32 vcc, s66, v8
	v_addc_co_u32_e32 v4, vcc, 0, v4, vcc
	v_cmp_le_u32_e32 vcc, s66, v5
	v_addc_co_u32_e32 v4, vcc, 0, v4, vcc
	s_and_b64 vcc, exec, s[82:83]
	s_cbranch_vccnz .LBB0_580
	v_cmp_le_u32_e32 vcc, s66, v33
	v_addc_co_u32_e32 v4, vcc, 0, v4, vcc
	v_cmp_le_u32_e32 vcc, s66, v41
	v_addc_co_u32_e32 v4, vcc, 0, v4, vcc
	v_cmp_le_u32_e32 vcc, s66, v32
	v_addc_co_u32_e32 v4, vcc, 0, v4, vcc
	v_cmp_le_u32_e32 vcc, s66, v42
	v_addc_co_u32_e32 v4, vcc, 0, v4, vcc
	v_cmp_le_u32_e32 vcc, s66, v29
	v_addc_co_u32_e32 v4, vcc, 0, v4, vcc
	v_cmp_le_u32_e32 vcc, s66, v30
	v_addc_co_u32_e32 v4, vcc, 0, v4, vcc
	v_cmp_le_u32_e32 vcc, s66, v28
	v_addc_co_u32_e32 v4, vcc, 0, v4, vcc
	v_cmp_le_u32_e32 vcc, s66, v31
	v_addc_co_u32_e32 v4, vcc, 0, v4, vcc
	s_and_b64 vcc, exec, s[78:79]
	s_cbranch_vccz .LBB0_581

; DI void select_row(const float* SC, unsigned* dmask, int b, int t, int lane) {
;     ...
;     if (!hit) {
;     ...
;             const unsigned cand = T | (1u << bit); int cnt; SEL_COUNT(cand, cnt);
;             if (cnt >= 256) { T = cand; if (cnt == 256) { hit = true; break; } }
;         }
;     }
.LBB0_577:
	v_cmp_le_u32_e32 vcc, s66, v15
	v_addc_co_u32_e32 v4, vcc, 0, v4, vcc
	v_cmp_le_u32_e32 vcc, s66, v16
	v_addc_co_u32_e32 v4, vcc, 0, v4, vcc
	v_cmp_le_u32_e32 vcc, s66, v19
	v_addc_co_u32_e32 v4, vcc, 0, v4, vcc
	v_cmp_le_u32_e32 vcc, s66, v20
	v_addc_co_u32_e32 v4, vcc, 0, v4, vcc
	v_cmp_le_u32_e32 vcc, s66, v13
	v_addc_co_u32_e32 v4, vcc, 0, v4, vcc
	v_cmp_le_u32_e32 vcc, s66, v14
	v_addc_co_u32_e32 v4, vcc, 0, v4, vcc
	v_cmp_le_u32_e32 vcc, s66, v12
	v_addc_co_u32_e32 v4, vcc, 0, v4, vcc
	v_cmp_le_u32_e32 vcc, s66, v17
	v_addc_co_u32_e32 v4, vcc, 0, v4, vcc
.LBB0_578:
	s_nop 1
	v_add_u32_dpp v4, v4, v4 row_shr:1 row_mask:0xf bank_mask:0xf bound_ctrl:1
	s_nop 0
	v_add_u32_dpp v4, v4, v4 row_shr:2 row_mask:0xf bank_mask:0xf bound_ctrl:1
	s_nop 1
	v_add_u32_dpp v4, v4, v4 row_shr:4 row_mask:0xf bank_mask:0xf bound_ctrl:1
	s_nop 1
	v_add_u32_dpp v4, v4, v4 row_shr:8 row_mask:0xf bank_mask:0xf bound_ctrl:1
	s_nop 1
	v_add_u32_dpp v4, v4, v4 row_bcast:15 row_mask:0xa bank_mask:0xf
	s_nop 1
	v_add_u32_dpp v4, v4, v4 row_bcast:31 row_mask:0xc bank_mask:0xf
	s_nop 0
	v_readlane_b32 s14, v4, 63
	s_cmpk_lt_i32 s14, 0x100
	s_cbranch_scc1 .Lsel_rej
	s_mov_b32 s56, s66
	s_cmpk_eq_i32 s14, 0x100
	s_cbranch_scc1 .Lsel_hit
.Lsel_rej:
	s_add_i32 s57, s57, -1
	s_cmp_ge_i32 s57, 0
	s_cbranch_scc1 .LBB0_574
	v_mov_b32_e32 v2, s56
	s_branch .LBB0_582
.Lsel_hit:
	s_mov_b64 s[8:9], -1
	v_mov_b32_e32 v2, s56
	s_branch .LBB0_582

.LBB0_581:
	v_cmp_le_u32_e32 vcc, s66, v24
	v_addc_co_u32_e32 v4, vcc, 0, v4, vcc
	v_cmp_le_u32_e32 vcc, s66, v25
	v_addc_co_u32_e32 v4, vcc, 0, v4, vcc
	v_cmp_le_u32_e32 vcc, s66, v26
	v_addc_co_u32_e32 v4, vcc, 0, v4, vcc
	v_cmp_le_u32_e32 vcc, s66, v27
	v_addc_co_u32_e32 v4, vcc, 0, v4, vcc
	v_cmp_le_u32_e32 vcc, s66, v21
	v_addc_co_u32_e32 v4, vcc, 0, v4, vcc
	v_cmp_le_u32_e32 vcc, s66, v22
	v_addc_co_u32_e32 v4, vcc, 0, v4, vcc
	v_cmp_le_u32_e32 vcc, s66, v18
	v_addc_co_u32_e32 v4, vcc, 0, v4, vcc
	v_cmp_le_u32_e32 vcc, s66, v23
	v_addc_co_u32_e32 v4, vcc, 0, v4, vcc
	s_and_b64 vcc, exec, s[76:77]
	s_cbranch_vccz .LBB0_577
	s_branch .LBB0_578
